# one static s_setprio 1 for waves 4-7 at the entry of the FoX-attention and dilated-attention phases (reset to 0 at phase exit)
# baseline (speedup 1.0000x reference)
.LBB0_82:
	s_mov_b32 s1, 0x8000
	v_add_co_u32_e32 v2, vcc, s1, v0
	s_mov_b32 s1, 0xa000
	s_nop 0
	v_addc_co_u32_e32 v3, vcc, 0, v1, vcc
	v_add_co_u32_e32 v4, vcc, s1, v0
	s_mov_b32 s1, 0xc000
	s_nop 0
	v_addc_co_u32_e32 v5, vcc, 0, v1, vcc
	global_load_dwordx4 v[96:99], v[2:3], off
	global_load_dwordx4 v[102:105], v[4:5], off
	v_add_co_u32_e32 v2, vcc, s1, v0
	s_mov_b32 s1, 0xe000
	s_nop 0
	v_addc_co_u32_e32 v3, vcc, 0, v1, vcc
	v_add_co_u32_e32 v4, vcc, s1, v0
	s_mov_b32 s1, 0x10000
	s_nop 0
	v_addc_co_u32_e32 v5, vcc, 0, v1, vcc
	global_load_dwordx4 v[106:109], v[2:3], off
	global_load_dwordx4 v[110:113], v[4:5], off
	v_add_co_u32_e32 v2, vcc, s1, v0
	s_mov_b32 s1, 0x12000
	s_nop 0
	v_addc_co_u32_e32 v3, vcc, 0, v1, vcc
	v_add_co_u32_e32 v4, vcc, s1, v0
	s_mov_b32 s1, 0x14000
	s_nop 0
	v_addc_co_u32_e32 v5, vcc, 0, v1, vcc
	global_load_dwordx4 v[114:117], v[2:3], off
	global_load_dwordx4 v[118:121], v[4:5], off
	v_add_co_u32_e32 v2, vcc, s1, v0
	s_mov_b32 s1, 0x16000
	s_nop 0
	v_addc_co_u32_e32 v3, vcc, 0, v1, vcc
	v_add_co_u32_e32 v0, vcc, s1, v0
	s_mul_i32 s1, s21, 0xc0000
	s_nop 0
	v_addc_co_u32_e32 v1, vcc, 0, v1, vcc
	global_load_dwordx4 v[122:125], v[2:3], off
	global_load_dwordx4 v[126:129], v[0:1], off
	s_mul_hi_u32 s6, s20, 0xc0000
	s_add_i32 s6, s6, s1
	s_add_u32 s64, s44, 0x3b800000
	v_readlane_b32 s28, v242, 63
	s_addc_u32 s65, s45, 0
	s_lshl_b32 s7, s28, 7
	s_add_i32 s78, s7, 0
	s_lshl_b32 s7, s28, 12
	s_add_i32 s79, s7, 0
	s_mul_i32 s1, s20, 0xc0000
	s_lshl_b32 s69, s28, 5
	s_add_i32 s78, s78, 0x18400
	s_add_i32 s79, s79, 0x18800
	v_readlane_b32 s20, v242, 45
	v_readlane_b32 s21, v242, 46
	s_add_u32 s7, s12, s20
	s_addc_u32 s12, s13, s21
	v_readlane_b32 s13, v242, 47
	s_add_u32 s50, s7, s13
	s_addc_u32 s51, s12, 0
	s_add_u32 s42, s64, s1
	s_addc_u32 s43, s65, s6
	s_lshl_b32 s1, s28, 13
	s_cmp_lt_i32 s28, 4
	s_cselect_b64 s[12:13], -1, 0
	s_cmp_lt_i32 s28, 3
	s_cselect_b64 s[20:21], -1, 0
	s_cmp_lt_i32 s28, 2
	s_cselect_b64 s[22:23], -1, 0
	s_cmp_lt_i32 s28, 1
	s_cselect_b64 s[24:25], -1, 0
	s_cmp_lt_i32 s28, 0
	s_cselect_b64 s[40:41], -1, 0
	s_add_i32 s80, s1, 0
	v_readlane_b32 s1, v242, 21
	s_mov_b32 s66, s1
	v_readlane_b32 s81, v242, 37
	v_readlane_b32 s67, v242, 34
	v_readlane_b32 s84, v242, 20
	v_readlane_b32 s89, v243, 63
	s_waitcnt lgkmcnt(0)
	v_lshlrev_b32_e32 v244, 2, v225
	global_load_dword v245, v244, s[2:3]
	v_and_b32_e32 v246, 0xff, v225
	v_lshlrev_b32_e32 v246, 2, v246
	global_load_dword v247, v246, s[2:3] offset:2048
	s_waitcnt vmcnt(0)
	v_add_u32_e32 v244, 0x21000, v244
	ds_write_b32 v244, v245
	v_add_u32_e32 v246, 0x21800, v246
	ds_write_b32 v246, v247
	s_waitcnt lgkmcnt(0)
	s_barrier
	s_mov_b32 s100, 0
	v_readfirstlane_b32 s101, v225
	s_lshr_b32 s101, s101, 6
	s_cmp_ge_u32 s101, 4
	s_cbranch_scc0 .Lmy_prio_b
	s_setprio 1
.Lmy_prio_b:
	s_branch .LBB0_84
.LBB0_83:
	s_mov_b32 s100, 1
	s_or_b64 exec, exec, s[28:29]
	s_and_b64 vcc, exec, s[70:71]
	s_mov_b32 s66, s54
	s_mov_b32 s67, s47
	s_mov_b32 s84, s52
	s_mov_b64 s[42:43], s[72:73]
	s_mov_b64 s[50:51], s[6:7]
	s_mov_b32 s89, s34
	s_waitcnt lgkmcnt(0)
	s_barrier
	s_cbranch_vccnz .LBB0_134

.LBB0_134:
	s_setprio 0
	s_mov_b64 s[2:3], 0

.LBB0_163:
	s_ashr_i32 s99, s98, 31
	s_lshl_b64 s[50:51], s[98:99], 19
	s_add_u32 s84, s8, s50
	s_addc_u32 s85, s9, s51
	s_and_b64 s[50:51], s[6:7], exec
	s_cselect_b32 s29, s85, s61
	s_cselect_b32 s31, s84, s60
	s_ashr_i32 s93, s92, 31
	s_lshl_b64 s[50:51], s[92:93], 19
	s_add_u32 s50, s10, s50
	s_addc_u32 s51, s11, s51
	s_and_b64 s[54:55], s[6:7], exec
	s_cselect_b32 s34, s51, s95
	s_cselect_b32 s47, s50, s94
	s_add_u32 vcc_lo, s60, 0x40080
	s_addc_u32 vcc_hi, s61, 0
	s_add_u32 s52, s94, 0x100
	v_mov_b32_e32 v0, 0
	s_addc_u32 s54, s95, 0
	s_mov_b32 s55, -2
	v_mov_b32_e32 v1, v0
	v_mov_b32_e32 v2, v0
	v_mov_b32_e32 v3, v0
	v_mov_b32_e32 v4, v0
	v_mov_b32_e32 v5, v0
	v_mov_b32_e32 v6, v0
	v_mov_b32_e32 v7, v0
	v_mov_b32_e32 v16, v0
	v_mov_b32_e32 v17, v0
	v_mov_b32_e32 v18, v0
	v_mov_b32_e32 v19, v0
	v_mov_b32_e32 v20, v0
	v_mov_b32_e32 v21, v0
	v_mov_b32_e32 v22, v0
	v_mov_b32_e32 v23, v0
	v_mov_b32_e32 v32, v0
	v_mov_b32_e32 v33, v0
	v_mov_b32_e32 v34, v0
	v_mov_b32_e32 v35, v0
	v_mov_b32_e32 v36, v0
	v_mov_b32_e32 v37, v0
	v_mov_b32_e32 v38, v0
	v_mov_b32_e32 v39, v0
	v_mov_b32_e32 v48, v0
	v_mov_b32_e32 v49, v0
	v_mov_b32_e32 v50, v0
	v_mov_b32_e32 v51, v0
	v_mov_b32_e32 v52, v0
	v_mov_b32_e32 v53, v0
	v_mov_b32_e32 v54, v0
	v_mov_b32_e32 v55, v0
	v_mov_b32_e32 v8, v0
	v_mov_b32_e32 v9, v0
	v_mov_b32_e32 v10, v0
	v_mov_b32_e32 v11, v0
	v_mov_b32_e32 v12, v0
	v_mov_b32_e32 v13, v0
	v_mov_b32_e32 v14, v0
	v_mov_b32_e32 v15, v0
	v_mov_b32_e32 v24, v0
	v_mov_b32_e32 v25, v0
	v_mov_b32_e32 v26, v0
	v_mov_b32_e32 v27, v0
	v_mov_b32_e32 v28, v0
	v_mov_b32_e32 v29, v0
	v_mov_b32_e32 v30, v0
	v_mov_b32_e32 v31, v0
	v_mov_b32_e32 v40, v0
	v_mov_b32_e32 v41, v0
	v_mov_b32_e32 v42, v0
	v_mov_b32_e32 v43, v0
	v_mov_b32_e32 v44, v0
	v_mov_b32_e32 v45, v0
	v_mov_b32_e32 v46, v0
	v_mov_b32_e32 v47, v0
	v_mov_b32_e32 v56, v0
	v_mov_b32_e32 v57, v0
	v_mov_b32_e32 v58, v0
	v_mov_b32_e32 v59, v0
	v_mov_b32_e32 v60, v0
	v_mov_b32_e32 v61, v0
	v_mov_b32_e32 v62, v0
	v_mov_b32_e32 v63, v0
	v_mov_b32_e32 v64, v0
	v_mov_b32_e32 v65, v0
	v_mov_b32_e32 v66, v0
	v_mov_b32_e32 v67, v0
	v_mov_b32_e32 v68, v0
	v_mov_b32_e32 v69, v0
	v_mov_b32_e32 v70, v0
	v_mov_b32_e32 v71, v0
	s_nop 0
	v_mov_b32_e32 v80, v0
	v_mov_b32_e32 v81, v0
	v_mov_b32_e32 v82, v0
	v_mov_b32_e32 v83, v0
	v_mov_b32_e32 v84, v0
	v_mov_b32_e32 v85, v0
	v_mov_b32_e32 v86, v0
	v_mov_b32_e32 v87, v0
	v_mov_b32_e32 v96, v0
	v_mov_b32_e32 v97, v0
	v_mov_b32_e32 v98, v0
	v_mov_b32_e32 v99, v0
	v_mov_b32_e32 v102, v0
	v_mov_b32_e32 v103, v0
	v_mov_b32_e32 v104, v0
	v_mov_b32_e32 v105, v0
	v_mov_b32_e32 v114, v0
	v_mov_b32_e32 v115, v0
	v_mov_b32_e32 v116, v0
	v_mov_b32_e32 v117, v0
	v_mov_b32_e32 v118, v0
	v_mov_b32_e32 v119, v0
	v_mov_b32_e32 v120, v0
	v_mov_b32_e32 v121, v0
	v_mov_b32_e32 v72, v0
	v_mov_b32_e32 v73, v0
	v_mov_b32_e32 v74, v0
	v_mov_b32_e32 v75, v0
	v_mov_b32_e32 v76, v0
	v_mov_b32_e32 v77, v0
	v_mov_b32_e32 v78, v0
	v_mov_b32_e32 v79, v0
	v_mov_b32_e32 v88, v0
	v_mov_b32_e32 v89, v0
	v_mov_b32_e32 v90, v0
	v_mov_b32_e32 v91, v0
	v_mov_b32_e32 v92, v0
	v_mov_b32_e32 v93, v0
	v_mov_b32_e32 v94, v0
	v_mov_b32_e32 v95, v0
	v_mov_b32_e32 v106, v0
	v_mov_b32_e32 v107, v0
	v_mov_b32_e32 v108, v0
	v_mov_b32_e32 v109, v0
	v_mov_b32_e32 v110, v0
	v_mov_b32_e32 v111, v0
	v_mov_b32_e32 v112, v0
	v_mov_b32_e32 v113, v0
	v_mov_b32_e32 v122, v0
	v_mov_b32_e32 v123, v0
	v_mov_b32_e32 v124, v0
	v_mov_b32_e32 v125, v0
	v_mov_b32_e32 v126, v0
	v_mov_b32_e32 v127, v0
	v_mov_b32_e32 v128, v0
	v_mov_b32_e32 v129, v0
	s_nop 0

.LBB0_222:
	s_and_b64 vcc, exec, s[42:43]
	s_cbranch_vccz .LBB0_368
	s_getreg_b32 s1, hwreg(HW_REG_XCC_ID, 0, 4)
	v_cmp_eq_u32_e32 vcc, 0, v225
	s_waitcnt lgkmcnt(0)
	s_and_saveexec_b64 s[2:3], vcc
	v_mov_b32_e32 v0, s46
	ds_write_b32 v0, v215
	s_or_b64 exec, exec, s[2:3]
	s_add_u32 s65, s44, 0xb800000
	s_addc_u32 s70, s45, 0
	s_add_u32 s14, s44, 0x13800000
	s_addc_u32 s15, s45, 0
	s_add_u32 s71, s44, 0x1b800000
	s_addc_u32 s72, s45, 0
	s_add_u32 s73, s44, 0x2c000000
	s_addc_u32 s64, s45, 0
	s_add_u32 s12, s44, 0x23800000
	s_addc_u32 s13, s45, 0
	s_add_u32 s4, s44, 0x2b800000
	s_addc_u32 s5, s45, 0
	s_add_u32 s26, s44, 0x2bc00000
	v_readlane_b32 s2, v242, 2
	s_addc_u32 s27, s45, 0
	v_readlane_b32 s3, v242, 3
	s_mov_b32 s6, s2
	s_ashr_i32 s7, s2, 31
	s_lshl_b64 s[2:3], s[6:7], 17
	s_add_u32 s2, s44, s2
	s_addc_u32 s3, s45, s3
	s_add_u32 s35, s2, 0xc0000
	s_mov_b32 s2, s6
	s_addc_u32 s80, s3, 0
	v_writelane_b32 v242, s2, 2
	s_waitcnt vmcnt(0) lgkmcnt(0)
	s_barrier
	v_writelane_b32 v242, s3, 3
	s_lshl_b32 s2, s6, 9
	s_ashr_i32 s3, s2, 31
	s_lshl_b64 s[2:3], s[2:3], 2
	s_add_u32 s2, s44, s2
	s_addc_u32 s3, s45, s3
	s_add_u32 s6, s2, 0x100000
	s_addc_u32 s7, s3, 0
	s_and_b32 s81, s1, 7
	s_lshl_b32 s2, s81, 8
	s_add_u32 s58, s6, s2
	s_addc_u32 s59, s7, 0
	s_add_i32 s2, s1, 1
	s_and_b32 s2, s2, 7
	s_lshl_b32 s3, s2, 8
	s_add_u32 s74, s6, s3
	s_addc_u32 s75, s7, 0
	s_add_i32 s3, s1, 2
	s_and_b32 s3, s3, 7
	s_lshl_b32 s8, s3, 8
	s_add_u32 s76, s6, s8
	s_addc_u32 s77, s7, 0
	s_add_i32 s8, s1, 3
	s_and_b32 s8, s8, 7
	v_writelane_b32 v241, s8, 10
	s_lshl_b32 s8, s8, 8
	s_add_u32 s8, s6, s8
	s_addc_u32 s9, s7, 0
	v_writelane_b32 v241, s8, 12
	s_nop 1
	v_writelane_b32 v241, s9, 13
	s_xor_b32 s8, s81, 4
	v_writelane_b32 v241, s8, 14
	s_lshl_b32 s8, s8, 8
	s_add_u32 s8, s6, s8
	s_addc_u32 s9, s7, 0
	v_writelane_b32 v241, s8, 15
	s_nop 1
	v_writelane_b32 v241, s9, 16
	s_add_i32 s8, s1, 5
	s_and_b32 s8, s8, 7
	v_writelane_b32 v241, s8, 17
	s_lshl_b32 s8, s8, 8
	s_add_u32 s8, s6, s8
	s_addc_u32 s9, s7, 0
	v_writelane_b32 v241, s8, 18
	s_nop 1
	v_writelane_b32 v241, s9, 19
	s_add_i32 s8, s1, 6
	s_and_b32 s8, s8, 7
	v_writelane_b32 v241, s8, 20
	s_lshl_b32 s8, s8, 8
	s_add_u32 s8, s6, s8
	s_addc_u32 s9, s7, 0
	v_writelane_b32 v241, s8, 21
	s_add_i32 s1, s1, -1
	s_and_b32 s1, s1, 7
	v_writelane_b32 v241, s9, 22
	v_writelane_b32 v241, s1, 23
	s_lshl_b32 s1, s1, 8
	s_add_u32 s6, s6, s1
	s_addc_u32 s7, s7, 0
	v_writelane_b32 v241, s6, 24
	s_lshl_b32 s98, s81, 9
	s_nop 0
	v_writelane_b32 v241, s7, 25
	v_readfirstlane_b32 s100, v225
	s_lshr_b32 s100, s100, 6
	s_cmp_ge_u32 s100, 4
	s_cbranch_scc0 .Lmy_prio_f
	s_setprio 1
.Lmy_prio_f:
	s_branch .LBB0_227
.LBB0_226:
	s_or_b64 exec, exec, s[6:7]
	s_waitcnt lgkmcnt(0)
	s_barrier

.LBB0_368:
	s_setprio 0
	s_waitcnt lgkmcnt(0)
	v_readlane_b32 s2, v241, 6
	v_readlane_b32 s3, v241, 7
	s_and_b64 vcc, exec, s[2:3]
	s_cbranch_vccz .LBB0_381
	s_mov_b64 s[2:3], -1
	v_writelane_b32 v241, s2, 0
	s_nop 1
	v_writelane_b32 v241, s3, 1
	s_mov_b64 s[2:3], -1
	v_readlane_b32 s1, v241, 2
	s_cmp_gt_i32 s1, 0
	s_cbranch_scc0 .LBB0_383
	v_readlane_b32 s2, v242, 2
	v_readlane_b32 s3, v242, 3
	s_cmp_eq_u32 s2, 0
	s_cselect_b32 s1, 0x110000, 0
	v_readlane_b32 s2, v242, 13
	s_add_u32 s66, s44, s1
	v_readlane_b32 s3, v242, 14
	s_addc_u32 s67, s45, 0
	s_andn2_b64 vcc, exec, s[2:3]
	s_mov_b64 s[2:3], -1
	s_cbranch_vccnz .LBB0_372
	v_readlane_b32 s2, v242, 2
	v_readlane_b32 s3, v242, 3
	s_ashr_i32 s3, s2, 31
	v_writelane_b32 v242, s2, 2
	s_nop 1
	v_writelane_b32 v242, s3, 3
	s_mov_b64 s[2:3], 0

.Lmy_st_done_cd:
	s_add_u32 s90, s2, s100
	s_addc_u32 s91, s3, 0
	s_waitcnt vmcnt(24)
	s_waitcnt lgkmcnt(0)
	s_barrier
	s_setprio 1
	s_waitcnt lgkmcnt(0)
	v_mfma_f32_16x16x32_bf16 v[60:63], v[144:147], v[182:185], 0
	v_mfma_f32_16x16x32_bf16 v[56:59], v[158:161], v[182:185], 0
	v_mfma_f32_16x16x32_bf16 v[44:47], v[144:147], v[190:193], 0
	v_mfma_f32_16x16x32_bf16 v[40:43], v[158:161], v[190:193], 0
	v_mfma_f32_16x16x32_bf16 v[28:31], v[144:147], v[198:201], 0
	v_mfma_f32_16x16x32_bf16 v[24:27], v[158:161], v[198:201], 0
	v_mfma_f32_16x16x32_bf16 v[12:15], v[144:147], v[208:211], 0
	v_mfma_f32_16x16x32_bf16 v[8:11], v[158:161], v[208:211], 0
	v_mfma_f32_16x16x32_bf16 v[60:63], v[148:151], v[186:189], v[60:63]
	v_mfma_f32_16x16x32_bf16 v[56:59], v[162:165], v[186:189], v[56:59]
	v_mfma_f32_16x16x32_bf16 v[44:47], v[148:151], v[194:197], v[44:47]
	v_mfma_f32_16x16x32_bf16 v[40:43], v[162:165], v[194:197], v[40:43]
	v_mfma_f32_16x16x32_bf16 v[28:31], v[148:151], v[202:205], v[28:31]
	v_mfma_f32_16x16x32_bf16 v[24:27], v[162:165], v[202:205], v[24:27]
	v_mfma_f32_16x16x32_bf16 v[12:15], v[148:151], v[226:229], v[12:15]
	v_mfma_f32_16x16x32_bf16 v[8:11], v[162:165], v[226:229], v[8:11]
	s_setprio 0
	s_setprio 1
	v_mfma_f32_16x16x32_bf16 v[52:55], v[166:169], v[182:185], 0
	v_mfma_f32_16x16x32_bf16 v[48:51], v[174:177], v[182:185], 0
	v_mfma_f32_16x16x32_bf16 v[36:39], v[166:169], v[190:193], 0
	v_mfma_f32_16x16x32_bf16 v[32:35], v[174:177], v[190:193], 0
	v_mfma_f32_16x16x32_bf16 v[20:23], v[166:169], v[198:201], 0
	v_mfma_f32_16x16x32_bf16 v[16:19], v[174:177], v[198:201], 0
	v_mfma_f32_16x16x32_bf16 v[4:7], v[166:169], v[208:211], 0
	v_mfma_f32_16x16x32_bf16 v[0:3], v[174:177], v[208:211], 0
	v_mfma_f32_16x16x32_bf16 v[52:55], v[170:173], v[186:189], v[52:55]
	v_mfma_f32_16x16x32_bf16 v[48:51], v[178:181], v[186:189], v[48:51]
	v_mfma_f32_16x16x32_bf16 v[36:39], v[170:173], v[194:197], v[36:39]
	v_mfma_f32_16x16x32_bf16 v[32:35], v[178:181], v[194:197], v[32:35]
	v_mfma_f32_16x16x32_bf16 v[20:23], v[170:173], v[202:205], v[20:23]
	v_mfma_f32_16x16x32_bf16 v[16:19], v[178:181], v[202:205], v[16:19]
	v_mfma_f32_16x16x32_bf16 v[4:7], v[170:173], v[226:229], v[4:7]
	v_mfma_f32_16x16x32_bf16 v[0:3], v[178:181], v[226:229], v[0:3]
	s_setprio 0
	s_barrier
	s_add_i32 s1, 0, 0x18000
	v_add_u32_e32 v100, s1, v154
	s_add_i32 s33, 0, 0x1c000
	ds_read_b128 v[144:147], v100
	ds_read_b128 v[148:151], v100 offset:1024
	ds_read_b128 v[158:161], v100 offset:2048
	ds_read_b128 v[162:165], v100 offset:3072
	v_add_u32_e32 v100, s33, v154
	ds_read_b128 v[166:169], v100
	ds_read_b128 v[170:173], v100 offset:1024
	ds_read_b128 v[174:177], v100 offset:2048
	ds_read_b128 v[178:181], v100 offset:3072
	s_add_u32 s28, s28, 0x40000
	s_addc_u32 s29, s29, 0
	s_mov_b32 m0, s61
	v_lshl_add_u64 v[234:235], s[28:29], 0, v[130:131]
	ds_read_b128 v[182:185], v156 offset:32768
	ds_read_b128 v[186:189], v156 offset:33792
	ds_read_b128 v[190:193], v156 offset:34816
	ds_read_b128 v[194:197], v156 offset:35840
	ds_read_b128 v[198:201], v156 offset:36864
	ds_read_b128 v[202:205], v156 offset:37888
	ds_read_b128 v[208:211], v156 offset:38912
	ds_read_b128 v[226:229], v156 offset:39936
	global_load_lds_dwordx4 v[234:235], off
	v_lshl_add_u64 v[234:235], s[28:29], 0, v[134:135]
	s_mov_b32 m0, s69
	s_nop 0
	global_load_lds_dwordx4 v[234:235], off
	s_lshl_b32 s46, s40, 8
	s_add_i32 s46, s46, s84
	v_or_b32_e32 v100, s46, v139
	v_lshlrev_b32_e32 v100, 2, v100
	global_load_dword v236, v100, s[66:67]
	global_load_dword v237, v100, s[66:67] offset:64
	global_load_dword v238, v100, s[66:67] offset:128
	global_load_dword v239, v100, s[66:67] offset:192
	global_load_dword v240, v100, s[66:67] offset:512
	global_load_dword v244, v100, s[66:67] offset:576
	global_load_dword v245, v100, s[66:67] offset:640
	global_load_dword v246, v100, s[66:67] offset:704
	s_waitcnt vmcnt(24)
	s_waitcnt lgkmcnt(0)
	s_barrier
	s_setprio 1
	s_waitcnt lgkmcnt(0)
	v_mfma_f32_16x16x32_bf16 v[126:129], v[144:147], v[182:185], v[126:129]
	v_mfma_f32_16x16x32_bf16 v[122:125], v[158:161], v[182:185], v[122:125]
	v_mfma_f32_16x16x32_bf16 v[110:113], v[144:147], v[190:193], v[110:113]
	v_mfma_f32_16x16x32_bf16 v[106:109], v[158:161], v[190:193], v[106:109]
	v_mfma_f32_16x16x32_bf16 v[92:95], v[144:147], v[198:201], v[92:95]
	v_mfma_f32_16x16x32_bf16 v[88:91], v[158:161], v[198:201], v[88:91]
	v_mfma_f32_16x16x32_bf16 v[76:79], v[144:147], v[208:211], v[76:79]
	v_mfma_f32_16x16x32_bf16 v[72:75], v[158:161], v[208:211], v[72:75]
	v_mfma_f32_16x16x32_bf16 v[126:129], v[148:151], v[186:189], v[126:129]
	v_mfma_f32_16x16x32_bf16 v[122:125], v[162:165], v[186:189], v[122:125]
	v_mfma_f32_16x16x32_bf16 v[110:113], v[148:151], v[194:197], v[110:113]
	v_mfma_f32_16x16x32_bf16 v[106:109], v[162:165], v[194:197], v[106:109]
	v_mfma_f32_16x16x32_bf16 v[92:95], v[148:151], v[202:205], v[92:95]
	v_mfma_f32_16x16x32_bf16 v[88:91], v[162:165], v[202:205], v[88:91]
	v_mfma_f32_16x16x32_bf16 v[76:79], v[148:151], v[226:229], v[76:79]
	v_mfma_f32_16x16x32_bf16 v[72:75], v[162:165], v[226:229], v[72:75]
	s_setprio 0
	s_setprio 1
	v_mfma_f32_16x16x32_bf16 v[118:121], v[166:169], v[182:185], v[118:121]
	v_mfma_f32_16x16x32_bf16 v[114:117], v[174:177], v[182:185], v[114:117]
	v_mfma_f32_16x16x32_bf16 v[102:105], v[166:169], v[190:193], v[102:105]
	v_mfma_f32_16x16x32_bf16 v[96:99], v[174:177], v[190:193], v[96:99]
	v_mfma_f32_16x16x32_bf16 v[84:87], v[166:169], v[198:201], v[84:87]
	v_mfma_f32_16x16x32_bf16 v[80:83], v[174:177], v[198:201], v[80:83]
	v_mfma_f32_16x16x32_bf16 v[68:71], v[166:169], v[208:211], v[68:71]
	v_mfma_f32_16x16x32_bf16 v[64:67], v[174:177], v[208:211], v[64:67]
	v_mfma_f32_16x16x32_bf16 v[118:121], v[170:173], v[186:189], v[118:121]
	v_mfma_f32_16x16x32_bf16 v[114:117], v[178:181], v[186:189], v[114:117]
	v_mfma_f32_16x16x32_bf16 v[102:105], v[170:173], v[194:197], v[102:105]
	v_mfma_f32_16x16x32_bf16 v[96:99], v[178:181], v[194:197], v[96:99]
	v_mfma_f32_16x16x32_bf16 v[84:87], v[170:173], v[202:205], v[84:87]
	v_mfma_f32_16x16x32_bf16 v[80:83], v[178:181], v[202:205], v[80:83]
	v_mfma_f32_16x16x32_bf16 v[68:71], v[170:173], v[226:229], v[68:71]
	v_mfma_f32_16x16x32_bf16 v[64:67], v[178:181], v[226:229], v[64:67]
	s_setprio 0
	s_barrier
	s_add_i32 s1, s1, s34
	v_lshl_add_u64 v[152:153], v[152:153], 0, s[86:87]
	s_mov_b32 m0, s1
	ds_read_b128 v[182:185], v156 offset:49152
	ds_read_b128 v[186:189], v156 offset:50176
	ds_read_b128 v[190:193], v156 offset:51200
	ds_read_b128 v[194:197], v156 offset:52224
	ds_read_b128 v[198:201], v156 offset:53248
	ds_read_b128 v[202:205], v156 offset:54272
	ds_read_b128 v[208:211], v156 offset:55296
	ds_read_b128 v[226:229], v156 offset:56320
	global_load_lds_dwordx4 v[152:153], off
	s_add_i32 m0, s1, 0x2000
	s_add_u32 s14, s14, 0x40080
	v_lshl_add_u64 v[152:153], v[212:213], 0, s[86:87]
	s_addc_u32 s15, s15, 0
	s_add_i32 s1, s33, s34
	global_load_lds_dwordx4 v[152:153], off
	v_lshl_add_u64 v[152:153], s[14:15], 0, v[132:133]
	s_mov_b32 m0, s1
	s_nop 0
	global_load_lds_dwordx4 v[152:153], off
	v_lshl_add_u64 v[152:153], s[14:15], 0, v[136:137]
	s_add_i32 m0, s1, 0x2000
	s_nop 0
	global_load_lds_dwordx4 v[152:153], off
	v_lshl_add_u64 v[152:153], v[230:231], 0, s[86:87]
	s_mov_b32 m0, s89
	s_nop 0
	global_load_lds_dwordx4 v[152:153], off
	v_lshl_add_u64 v[152:153], v[232:233], 0, s[86:87]
	s_mov_b32 m0, s92
	s_nop 0
	global_load_lds_dwordx4 v[152:153], off
	s_waitcnt vmcnt(16)
	s_waitcnt lgkmcnt(0)
	s_barrier
	s_setprio 1
	s_waitcnt lgkmcnt(0)
	v_mfma_f32_16x16x32_bf16 v[60:63], v[144:147], v[182:185], v[60:63]
	v_mfma_f32_16x16x32_bf16 v[56:59], v[158:161], v[182:185], v[56:59]
	v_mfma_f32_16x16x32_bf16 v[44:47], v[144:147], v[190:193], v[44:47]
	v_mfma_f32_16x16x32_bf16 v[40:43], v[158:161], v[190:193], v[40:43]
	v_mfma_f32_16x16x32_bf16 v[28:31], v[144:147], v[198:201], v[28:31]
	v_mfma_f32_16x16x32_bf16 v[24:27], v[158:161], v[198:201], v[24:27]
	v_mfma_f32_16x16x32_bf16 v[12:15], v[144:147], v[208:211], v[12:15]
	v_mfma_f32_16x16x32_bf16 v[8:11], v[158:161], v[208:211], v[8:11]
	v_mfma_f32_16x16x32_bf16 v[60:63], v[148:151], v[186:189], v[60:63]
	v_mfma_f32_16x16x32_bf16 v[56:59], v[162:165], v[186:189], v[56:59]
	v_mfma_f32_16x16x32_bf16 v[44:47], v[148:151], v[194:197], v[44:47]
	v_mfma_f32_16x16x32_bf16 v[40:43], v[162:165], v[194:197], v[40:43]
	v_mfma_f32_16x16x32_bf16 v[28:31], v[148:151], v[202:205], v[28:31]
	v_mfma_f32_16x16x32_bf16 v[24:27], v[162:165], v[202:205], v[24:27]
	v_mfma_f32_16x16x32_bf16 v[12:15], v[148:151], v[226:229], v[12:15]
	v_mfma_f32_16x16x32_bf16 v[8:11], v[162:165], v[226:229], v[8:11]
	s_setprio 0
	s_setprio 1
	v_mfma_f32_16x16x32_bf16 v[52:55], v[166:169], v[182:185], v[52:55]
	v_mfma_f32_16x16x32_bf16 v[48:51], v[174:177], v[182:185], v[48:51]
	v_mfma_f32_16x16x32_bf16 v[36:39], v[166:169], v[190:193], v[36:39]
	v_mfma_f32_16x16x32_bf16 v[32:35], v[174:177], v[190:193], v[32:35]
	v_mfma_f32_16x16x32_bf16 v[20:23], v[166:169], v[198:201], v[20:23]
	v_mfma_f32_16x16x32_bf16 v[16:19], v[174:177], v[198:201], v[16:19]
	v_mfma_f32_16x16x32_bf16 v[4:7], v[166:169], v[208:211], v[4:7]
	v_mfma_f32_16x16x32_bf16 v[0:3], v[174:177], v[208:211], v[0:3]
	v_mfma_f32_16x16x32_bf16 v[52:55], v[170:173], v[186:189], v[52:55]
	v_mfma_f32_16x16x32_bf16 v[48:51], v[178:181], v[186:189], v[48:51]
	v_mfma_f32_16x16x32_bf16 v[36:39], v[170:173], v[194:197], v[36:39]
	v_mfma_f32_16x16x32_bf16 v[32:35], v[178:181], v[194:197], v[32:35]
	v_mfma_f32_16x16x32_bf16 v[20:23], v[170:173], v[202:205], v[20:23]
	v_mfma_f32_16x16x32_bf16 v[16:19], v[178:181], v[202:205], v[16:19]
	v_mfma_f32_16x16x32_bf16 v[4:7], v[170:173], v[226:229], v[4:7]
	v_mfma_f32_16x16x32_bf16 v[0:3], v[178:181], v[226:229], v[0:3]
	s_setprio 0
	s_barrier
	s_add_i32 s73, s73, 2
	s_add_u32 s12, s12, 0x100
	s_addc_u32 s13, s13, 0
	s_add_u32 s54, s54, 0x100
	s_addc_u32 s55, s55, 0
.LBB0_396:
	s_add_u32 s1, s12, 0xfffc0080
	s_addc_u32 s14, s13, -1
	s_add_i32 s33, 0, 0x10000
	s_cmp_eq_u32 s73, 12
	s_cselect_b32 s29, s11, s14
	s_cselect_b32 s28, s30, s1
	v_add_u32_e32 v100, s33, v154
	s_cselect_b32 s15, s31, s55
	s_cselect_b32 s14, s47, s54
	s_add_i32 s1, 0, 0x14000
	ds_read_b128 v[144:147], v100
	ds_read_b128 v[148:151], v100 offset:1024
	ds_read_b128 v[158:161], v100 offset:2048
	ds_read_b128 v[162:165], v100 offset:3072
	v_add_u32_e32 v100, s1, v154
	ds_read_b128 v[166:169], v100
	ds_read_b128 v[170:173], v100 offset:1024
	ds_read_b128 v[174:177], v100 offset:2048
	ds_read_b128 v[178:181], v100 offset:3072
	v_lshl_add_u64 v[152:153], s[12:13], 0, v[140:141]
	s_add_i32 m0, s41, 0xc000
	ds_read_b128 v[182:185], v156
	ds_read_b128 v[186:189], v156 offset:1024
	ds_read_b128 v[190:193], v156 offset:2048
	ds_read_b128 v[194:197], v156 offset:3072
	ds_read_b128 v[198:201], v156 offset:4096
	ds_read_b128 v[202:205], v156 offset:5120
	ds_read_b128 v[208:211], v156 offset:6144
	ds_read_b128 v[226:229], v156 offset:7168
	global_load_lds_dwordx4 v[152:153], off
	v_lshl_add_u64 v[152:153], s[12:13], 0, v[142:143]
	s_add_i32 m0, s41, 0xe000
	s_nop 0
	global_load_lds_dwordx4 v[152:153], off
	s_waitcnt vmcnt(8)
	s_waitcnt lgkmcnt(0)
	s_barrier
	s_setprio 1
	s_waitcnt lgkmcnt(0)
	v_mfma_f32_16x16x32_bf16 v[126:129], v[144:147], v[182:185], v[126:129]
	v_mfma_f32_16x16x32_bf16 v[122:125], v[158:161], v[182:185], v[122:125]
	v_mfma_f32_16x16x32_bf16 v[110:113], v[144:147], v[190:193], v[110:113]
	v_mfma_f32_16x16x32_bf16 v[106:109], v[158:161], v[190:193], v[106:109]
	v_mfma_f32_16x16x32_bf16 v[92:95], v[144:147], v[198:201], v[92:95]
	v_mfma_f32_16x16x32_bf16 v[88:91], v[158:161], v[198:201], v[88:91]
	v_mfma_f32_16x16x32_bf16 v[76:79], v[144:147], v[208:211], v[76:79]
	v_mfma_f32_16x16x32_bf16 v[72:75], v[158:161], v[208:211], v[72:75]
	v_mfma_f32_16x16x32_bf16 v[126:129], v[148:151], v[186:189], v[126:129]
	v_mfma_f32_16x16x32_bf16 v[122:125], v[162:165], v[186:189], v[122:125]
	v_mfma_f32_16x16x32_bf16 v[110:113], v[148:151], v[194:197], v[110:113]
	v_mfma_f32_16x16x32_bf16 v[106:109], v[162:165], v[194:197], v[106:109]
	v_mfma_f32_16x16x32_bf16 v[92:95], v[148:151], v[202:205], v[92:95]
	v_mfma_f32_16x16x32_bf16 v[88:91], v[162:165], v[202:205], v[88:91]
	v_mfma_f32_16x16x32_bf16 v[76:79], v[148:151], v[226:229], v[76:79]
	v_mfma_f32_16x16x32_bf16 v[72:75], v[162:165], v[226:229], v[72:75]
	s_setprio 0
	s_setprio 1
	v_mfma_f32_16x16x32_bf16 v[118:121], v[166:169], v[182:185], v[118:121]
	v_mfma_f32_16x16x32_bf16 v[114:117], v[174:177], v[182:185], v[114:117]
	v_mfma_f32_16x16x32_bf16 v[102:105], v[166:169], v[190:193], v[102:105]
	v_mfma_f32_16x16x32_bf16 v[96:99], v[174:177], v[190:193], v[96:99]
	v_mfma_f32_16x16x32_bf16 v[84:87], v[166:169], v[198:201], v[84:87]
	v_mfma_f32_16x16x32_bf16 v[80:83], v[174:177], v[198:201], v[80:83]
	v_mfma_f32_16x16x32_bf16 v[68:71], v[166:169], v[208:211], v[68:71]
	v_mfma_f32_16x16x32_bf16 v[64:67], v[174:177], v[208:211], v[64:67]
	v_mfma_f32_16x16x32_bf16 v[118:121], v[170:173], v[186:189], v[118:121]
	v_mfma_f32_16x16x32_bf16 v[114:117], v[178:181], v[186:189], v[114:117]
	v_mfma_f32_16x16x32_bf16 v[102:105], v[170:173], v[194:197], v[102:105]
	v_mfma_f32_16x16x32_bf16 v[96:99], v[178:181], v[194:197], v[96:99]
	v_mfma_f32_16x16x32_bf16 v[84:87], v[170:173], v[202:205], v[84:87]
	v_mfma_f32_16x16x32_bf16 v[80:83], v[178:181], v[202:205], v[80:83]
	v_mfma_f32_16x16x32_bf16 v[68:71], v[170:173], v[226:229], v[68:71]
	v_mfma_f32_16x16x32_bf16 v[64:67], v[178:181], v[226:229], v[64:67]
	s_setprio 0
	s_barrier
	s_add_i32 s33, s33, s34
	v_lshl_add_u64 v[152:153], s[14:15], 0, v[132:133]
	s_mov_b32 m0, s33
	ds_read_b128 v[182:185], v156 offset:16384
	ds_read_b128 v[186:189], v156 offset:17408
	ds_read_b128 v[190:193], v156 offset:18432
	ds_read_b128 v[194:197], v156 offset:19456
	ds_read_b128 v[198:201], v156 offset:20480
	ds_read_b128 v[202:205], v156 offset:21504
	ds_read_b128 v[208:211], v156 offset:22528
	ds_read_b128 v[226:229], v156 offset:23552
	global_load_lds_dwordx4 v[152:153], off
	s_add_i32 m0, s33, 0x2000
	s_add_u32 s80, s14, 0x40000
	v_lshl_add_u64 v[212:213], s[14:15], 0, v[136:137]
	s_addc_u32 s81, s15, 0
	s_add_i32 s1, s1, s34
	global_load_lds_dwordx4 v[212:213], off
	v_lshl_add_u64 v[230:231], s[80:81], 0, v[132:133]
	s_mov_b32 m0, s1
	v_lshl_add_u64 v[232:233], s[28:29], 0, v[134:135]
	global_load_lds_dwordx4 v[230:231], off
	v_lshl_add_u64 v[230:231], s[80:81], 0, v[136:137]
	s_add_i32 m0, s1, 0x2000
	s_nop 0
	global_load_lds_dwordx4 v[230:231], off
	v_lshl_add_u64 v[230:231], s[28:29], 0, v[130:131]
	s_mov_b32 m0, s41
	s_nop 0
	global_load_lds_dwordx4 v[230:231], off
	s_mov_b32 m0, s60
	s_nop 0
	global_load_lds_dwordx4 v[232:233], off
	s_waitcnt vmcnt(8)
	s_waitcnt lgkmcnt(0)
	s_barrier
	s_setprio 1
	s_waitcnt lgkmcnt(0)
	v_mfma_f32_16x16x32_bf16 v[60:63], v[144:147], v[182:185], v[60:63]
	v_mfma_f32_16x16x32_bf16 v[56:59], v[158:161], v[182:185], v[56:59]
	v_mfma_f32_16x16x32_bf16 v[44:47], v[144:147], v[190:193], v[44:47]
	v_mfma_f32_16x16x32_bf16 v[40:43], v[158:161], v[190:193], v[40:43]
	v_mfma_f32_16x16x32_bf16 v[28:31], v[144:147], v[198:201], v[28:31]
	v_mfma_f32_16x16x32_bf16 v[24:27], v[158:161], v[198:201], v[24:27]
	v_mfma_f32_16x16x32_bf16 v[12:15], v[144:147], v[208:211], v[12:15]
	v_mfma_f32_16x16x32_bf16 v[8:11], v[158:161], v[208:211], v[8:11]
	v_mfma_f32_16x16x32_bf16 v[60:63], v[148:151], v[186:189], v[60:63]
	v_mfma_f32_16x16x32_bf16 v[56:59], v[162:165], v[186:189], v[56:59]
	v_mfma_f32_16x16x32_bf16 v[44:47], v[148:151], v[194:197], v[44:47]
	v_mfma_f32_16x16x32_bf16 v[40:43], v[162:165], v[194:197], v[40:43]
	v_mfma_f32_16x16x32_bf16 v[28:31], v[148:151], v[202:205], v[28:31]
	v_mfma_f32_16x16x32_bf16 v[24:27], v[162:165], v[202:205], v[24:27]
	v_mfma_f32_16x16x32_bf16 v[12:15], v[148:151], v[226:229], v[12:15]
	v_mfma_f32_16x16x32_bf16 v[8:11], v[162:165], v[226:229], v[8:11]
	s_setprio 0
	s_setprio 1
	v_mfma_f32_16x16x32_bf16 v[52:55], v[166:169], v[182:185], v[52:55]
	v_mfma_f32_16x16x32_bf16 v[48:51], v[174:177], v[182:185], v[48:51]
	v_mfma_f32_16x16x32_bf16 v[36:39], v[166:169], v[190:193], v[36:39]
	v_mfma_f32_16x16x32_bf16 v[32:35], v[174:177], v[190:193], v[32:35]
	v_mfma_f32_16x16x32_bf16 v[20:23], v[166:169], v[198:201], v[20:23]
	v_mfma_f32_16x16x32_bf16 v[16:19], v[174:177], v[198:201], v[16:19]
	v_mfma_f32_16x16x32_bf16 v[4:7], v[166:169], v[208:211], v[4:7]
	v_mfma_f32_16x16x32_bf16 v[0:3], v[174:177], v[208:211], v[0:3]
	v_mfma_f32_16x16x32_bf16 v[52:55], v[170:173], v[186:189], v[52:55]
	v_mfma_f32_16x16x32_bf16 v[48:51], v[178:181], v[186:189], v[48:51]
	v_mfma_f32_16x16x32_bf16 v[36:39], v[170:173], v[194:197], v[36:39]
	v_mfma_f32_16x16x32_bf16 v[32:35], v[178:181], v[194:197], v[32:35]
	v_mfma_f32_16x16x32_bf16 v[20:23], v[170:173], v[202:205], v[20:23]
	v_mfma_f32_16x16x32_bf16 v[16:19], v[178:181], v[202:205], v[16:19]
	v_mfma_f32_16x16x32_bf16 v[4:7], v[170:173], v[226:229], v[4:7]
	v_mfma_f32_16x16x32_bf16 v[0:3], v[178:181], v[226:229], v[0:3]
	s_setprio 0
	s_barrier
	s_add_i32 s1, 0, 0x18000
	v_add_u32_e32 v100, s1, v154
	s_add_i32 s33, 0, 0x1c000
	ds_read_b128 v[144:147], v100
	ds_read_b128 v[148:151], v100 offset:1024
	ds_read_b128 v[158:161], v100 offset:2048
	ds_read_b128 v[162:165], v100 offset:3072
	v_add_u32_e32 v100, s33, v154
	ds_read_b128 v[166:169], v100
	ds_read_b128 v[170:173], v100 offset:1024
	ds_read_b128 v[174:177], v100 offset:2048
	ds_read_b128 v[178:181], v100 offset:3072
	s_add_u32 s28, s28, 0x40000
	s_addc_u32 s29, s29, 0
	s_mov_b32 m0, s61
	v_lshl_add_u64 v[234:235], s[28:29], 0, v[130:131]
	ds_read_b128 v[182:185], v156 offset:32768
	ds_read_b128 v[186:189], v156 offset:33792
	ds_read_b128 v[190:193], v156 offset:34816
	ds_read_b128 v[194:197], v156 offset:35840
	ds_read_b128 v[198:201], v156 offset:36864
	ds_read_b128 v[202:205], v156 offset:37888
	ds_read_b128 v[208:211], v156 offset:38912
	ds_read_b128 v[226:229], v156 offset:39936
	global_load_lds_dwordx4 v[234:235], off
	v_lshl_add_u64 v[234:235], s[28:29], 0, v[134:135]
	s_mov_b32 m0, s69
	s_nop 0
	global_load_lds_dwordx4 v[234:235], off
	s_waitcnt vmcnt(8)
	s_waitcnt lgkmcnt(0)
	s_barrier
	s_setprio 1
	s_waitcnt lgkmcnt(0)
	v_mfma_f32_16x16x32_bf16 v[126:129], v[144:147], v[182:185], v[126:129]
	v_mfma_f32_16x16x32_bf16 v[122:125], v[158:161], v[182:185], v[122:125]
	v_mfma_f32_16x16x32_bf16 v[110:113], v[144:147], v[190:193], v[110:113]
	v_mfma_f32_16x16x32_bf16 v[106:109], v[158:161], v[190:193], v[106:109]
	v_mfma_f32_16x16x32_bf16 v[92:95], v[144:147], v[198:201], v[92:95]
	v_mfma_f32_16x16x32_bf16 v[88:91], v[158:161], v[198:201], v[88:91]
	v_mfma_f32_16x16x32_bf16 v[76:79], v[144:147], v[208:211], v[76:79]
	v_mfma_f32_16x16x32_bf16 v[72:75], v[158:161], v[208:211], v[72:75]
	v_mfma_f32_16x16x32_bf16 v[126:129], v[148:151], v[186:189], v[126:129]
	v_mfma_f32_16x16x32_bf16 v[122:125], v[162:165], v[186:189], v[122:125]
	v_mfma_f32_16x16x32_bf16 v[110:113], v[148:151], v[194:197], v[110:113]
	v_mfma_f32_16x16x32_bf16 v[106:109], v[162:165], v[194:197], v[106:109]
	v_mfma_f32_16x16x32_bf16 v[92:95], v[148:151], v[202:205], v[92:95]
	v_mfma_f32_16x16x32_bf16 v[88:91], v[162:165], v[202:205], v[88:91]
	v_mfma_f32_16x16x32_bf16 v[76:79], v[148:151], v[226:229], v[76:79]
	v_mfma_f32_16x16x32_bf16 v[72:75], v[162:165], v[226:229], v[72:75]
	s_setprio 0
	s_setprio 1
	v_mfma_f32_16x16x32_bf16 v[118:121], v[166:169], v[182:185], v[118:121]
	v_mfma_f32_16x16x32_bf16 v[114:117], v[174:177], v[182:185], v[114:117]
	v_mfma_f32_16x16x32_bf16 v[102:105], v[166:169], v[190:193], v[102:105]
	v_mfma_f32_16x16x32_bf16 v[96:99], v[174:177], v[190:193], v[96:99]
	v_mfma_f32_16x16x32_bf16 v[84:87], v[166:169], v[198:201], v[84:87]
	v_mfma_f32_16x16x32_bf16 v[80:83], v[174:177], v[198:201], v[80:83]
	v_mfma_f32_16x16x32_bf16 v[68:71], v[166:169], v[208:211], v[68:71]
	v_mfma_f32_16x16x32_bf16 v[64:67], v[174:177], v[208:211], v[64:67]
	v_mfma_f32_16x16x32_bf16 v[118:121], v[170:173], v[186:189], v[118:121]
	v_mfma_f32_16x16x32_bf16 v[114:117], v[178:181], v[186:189], v[114:117]
	v_mfma_f32_16x16x32_bf16 v[102:105], v[170:173], v[194:197], v[102:105]
	v_mfma_f32_16x16x32_bf16 v[96:99], v[178:181], v[194:197], v[96:99]
	v_mfma_f32_16x16x32_bf16 v[84:87], v[170:173], v[202:205], v[84:87]
	v_mfma_f32_16x16x32_bf16 v[80:83], v[178:181], v[202:205], v[80:83]
	v_mfma_f32_16x16x32_bf16 v[68:71], v[170:173], v[226:229], v[68:71]
	v_mfma_f32_16x16x32_bf16 v[64:67], v[178:181], v[226:229], v[64:67]
	s_setprio 0
	s_barrier
	s_add_i32 s1, s1, s34
	v_lshl_add_u64 v[152:153], v[152:153], 0, s[86:87]
	s_mov_b32 m0, s1
	ds_read_b128 v[182:185], v156 offset:49152
	ds_read_b128 v[186:189], v156 offset:50176
	ds_read_b128 v[190:193], v156 offset:51200
	ds_read_b128 v[194:197], v156 offset:52224
	ds_read_b128 v[198:201], v156 offset:53248
	ds_read_b128 v[202:205], v156 offset:54272
	ds_read_b128 v[208:211], v156 offset:55296
	ds_read_b128 v[226:229], v156 offset:56320
	global_load_lds_dwordx4 v[152:153], off
	s_add_i32 m0, s1, 0x2000
	s_add_u32 s14, s14, 0x40080
	v_lshl_add_u64 v[152:153], v[212:213], 0, s[86:87]
	s_addc_u32 s15, s15, 0
	s_add_i32 s1, s33, s34
	global_load_lds_dwordx4 v[152:153], off
	v_lshl_add_u64 v[152:153], s[14:15], 0, v[132:133]
	s_mov_b32 m0, s1
	s_nop 0
	global_load_lds_dwordx4 v[152:153], off
	v_lshl_add_u64 v[152:153], s[14:15], 0, v[136:137]
	s_add_i32 m0, s1, 0x2000
	s_nop 0
	global_load_lds_dwordx4 v[152:153], off
	v_lshl_add_u64 v[152:153], v[230:231], 0, s[86:87]
	s_mov_b32 m0, s89
	s_nop 0
	global_load_lds_dwordx4 v[152:153], off
	v_lshl_add_u64 v[152:153], v[232:233], 0, s[86:87]
	s_mov_b32 m0, s92
	s_nop 0
	global_load_lds_dwordx4 v[152:153], off
	s_waitcnt vmcnt(8)
	s_waitcnt lgkmcnt(0)
	s_barrier
	s_setprio 1
	s_waitcnt lgkmcnt(0)
	v_mfma_f32_16x16x32_bf16 v[60:63], v[144:147], v[182:185], v[60:63]
	v_mfma_f32_16x16x32_bf16 v[56:59], v[158:161], v[182:185], v[56:59]
	v_mfma_f32_16x16x32_bf16 v[44:47], v[144:147], v[190:193], v[44:47]
	v_mfma_f32_16x16x32_bf16 v[40:43], v[158:161], v[190:193], v[40:43]
	v_mfma_f32_16x16x32_bf16 v[28:31], v[144:147], v[198:201], v[28:31]
	v_mfma_f32_16x16x32_bf16 v[24:27], v[158:161], v[198:201], v[24:27]
	v_mfma_f32_16x16x32_bf16 v[12:15], v[144:147], v[208:211], v[12:15]
	v_mfma_f32_16x16x32_bf16 v[8:11], v[158:161], v[208:211], v[8:11]
	v_mfma_f32_16x16x32_bf16 v[60:63], v[148:151], v[186:189], v[60:63]
	v_mfma_f32_16x16x32_bf16 v[56:59], v[162:165], v[186:189], v[56:59]
	v_mfma_f32_16x16x32_bf16 v[44:47], v[148:151], v[194:197], v[44:47]
	v_mfma_f32_16x16x32_bf16 v[40:43], v[162:165], v[194:197], v[40:43]
	v_mfma_f32_16x16x32_bf16 v[28:31], v[148:151], v[202:205], v[28:31]
	v_mfma_f32_16x16x32_bf16 v[24:27], v[162:165], v[202:205], v[24:27]
	v_mfma_f32_16x16x32_bf16 v[12:15], v[148:151], v[226:229], v[12:15]
	v_mfma_f32_16x16x32_bf16 v[8:11], v[162:165], v[226:229], v[8:11]
	s_setprio 0
	s_setprio 1
	v_mfma_f32_16x16x32_bf16 v[52:55], v[166:169], v[182:185], v[52:55]
	v_mfma_f32_16x16x32_bf16 v[48:51], v[174:177], v[182:185], v[48:51]
	v_mfma_f32_16x16x32_bf16 v[36:39], v[166:169], v[190:193], v[36:39]
	v_mfma_f32_16x16x32_bf16 v[32:35], v[174:177], v[190:193], v[32:35]
	v_mfma_f32_16x16x32_bf16 v[20:23], v[166:169], v[198:201], v[20:23]
	v_mfma_f32_16x16x32_bf16 v[16:19], v[174:177], v[198:201], v[16:19]
	v_mfma_f32_16x16x32_bf16 v[4:7], v[166:169], v[208:211], v[4:7]
	v_mfma_f32_16x16x32_bf16 v[0:3], v[174:177], v[208:211], v[0:3]
	v_mfma_f32_16x16x32_bf16 v[52:55], v[170:173], v[186:189], v[52:55]
	v_mfma_f32_16x16x32_bf16 v[48:51], v[178:181], v[186:189], v[48:51]
	v_mfma_f32_16x16x32_bf16 v[36:39], v[170:173], v[194:197], v[36:39]
	v_mfma_f32_16x16x32_bf16 v[32:35], v[178:181], v[194:197], v[32:35]
	v_mfma_f32_16x16x32_bf16 v[20:23], v[170:173], v[202:205], v[20:23]
	v_mfma_f32_16x16x32_bf16 v[16:19], v[178:181], v[202:205], v[16:19]
	v_mfma_f32_16x16x32_bf16 v[4:7], v[170:173], v[226:229], v[4:7]
	v_mfma_f32_16x16x32_bf16 v[0:3], v[178:181], v[226:229], v[0:3]
	s_setprio 0
	s_barrier
	s_add_i32 s73, s73, 2
	s_add_u32 s12, s12, 0x100
	s_addc_u32 s13, s13, 0
	s_add_u32 s54, s54, 0x100
	s_addc_u32 s55, s55, 0
	s_cmp_gt_u32 s73, s97
	s_cbranch_scc0 .LBB0_396
